# v13 + GEMM unit-edge waits: in-proj epilogue-head vmcnt(0)->vmcnt(8) (rstd loads are 256 ops old), uq/ukv pre-hook loads issued together with one counted wait instead of two serialized round trips
# speedup vs baseline: 1.0005x; 1.0005x over previous
.LBB0_273:
	v_and_or_b32 v132, v211, 64, v163
	v_lshlrev_b32_e32 v132, 2, v132
	s_waitcnt vmcnt(8)
	ds_bpermute_b32 v178, v132, v177
	ds_bpermute_b32 v176, v132, v175
	ds_bpermute_b32 v174, v132, v177 offset:64
	ds_bpermute_b32 v172, v132, v175 offset:64
	ds_bpermute_b32 v170, v132, v177 offset:128
	ds_bpermute_b32 v168, v132, v175 offset:128
	ds_bpermute_b32 v166, v132, v177 offset:192
	ds_bpermute_b32 v162, v132, v175 offset:192
	v_add_u32_e32 v164, s3, v167
	s_cmp_gt_i32 s54, 5
	s_mov_b64 s[8:9], -1
	s_cbranch_scc1 .LBB0_276
	s_andn2_b64 vcc, exec, s[8:9]
	s_cbranch_vccz .LBB0_281

.LBB0_381:
	v_and_or_b32 v2, v211, 64, v153
	v_lshlrev_b32_e32 v2, 2, v2
	s_waitcnt vmcnt(8)
	ds_bpermute_b32 v178, v2, v175
	ds_bpermute_b32 v176, v2, v173
	ds_bpermute_b32 v174, v2, v175 offset:64
	ds_bpermute_b32 v172, v2, v173 offset:64
	ds_bpermute_b32 v170, v2, v175 offset:128
	ds_bpermute_b32 v168, v2, v173 offset:128
	ds_bpermute_b32 v166, v2, v175 offset:192
	ds_bpermute_b32 v162, v2, v173 offset:192
	v_add_u32_e32 v164, s3, v163
	s_cmp_gt_i32 s62, 5
	s_mov_b64 s[8:9], -1
	s_cbranch_scc1 .LBB0_384
	s_andn2_b64 vcc, exec, s[8:9]
	s_cbranch_vccz .LBB0_401

.LBB0_439:
	s_cmpk_lg_i32 s10, 0x300
	s_cbranch_scc1 .LBB0_438
	global_load_dwordx4 v[132:135], v[160:161], off offset:48
	global_load_dwordx4 v[136:139], v[160:161], off offset:32
	global_load_dwordx4 v[140:143], v[160:161], off offset:16
	global_load_dwordx4 v[168:171], v[160:161], off
	global_load_dwordx4 v[194:197], v[162:163], off offset:48
	global_load_dwordx4 v[198:201], v[162:163], off offset:32
	global_load_dwordx4 v[202:205], v[162:163], off offset:16
	global_load_dwordx4 v[214:217], v[162:163], off
	s_waitcnt vmcnt(4)
	v_add_f32_e32 v136, v136, v137
	v_add_f32_e32 v138, v138, v139
	v_mov_b32_e32 v172, v169
	v_mov_b32_e32 v173, v170
	v_mov_b32_e32 v169, v171
	v_mov_b32_e32 v170, v141
	v_mov_b32_e32 v171, v142
	v_mov_b32_e32 v141, v143
	v_pk_add_f32 v[168:169], v[172:173], v[168:169]
	v_pk_add_f32 v[140:141], v[170:171], v[140:141]
	v_pk_add_f32 v[168:169], v[168:169], v[168:169] op_sel:[0,1] op_sel_hi:[1,0]
	v_pk_add_f32 v[140:141], v[140:141], v[140:141] op_sel:[0,1] op_sel_hi:[1,0]
	v_mov_b32_e32 v169, v132
	v_mov_b32_e32 v141, v133
	v_mov_b32_e32 v137, v134
	v_mov_b32_e32 v139, v135
	v_pk_add_f32 v[132:133], v[168:169], v[140:141]
	v_pk_add_f32 v[134:135], v[136:137], v[138:139]
	s_nop 0
	v_pk_add_f32 v[132:133], v[132:133], v[134:135]
	s_nop 0
	v_add_f32_e32 v132, v132, v133
	v_fmamk_f32 v132, v132, 0x3a800000, v209
	v_cmp_gt_f32_e32 vcc, s20, v132
	v_mul_f32_e32 v133, 0x4f800000, v132
	s_nop 0
	v_cndmask_b32_e32 v132, v132, v133, vcc
	v_sqrt_f32_e32 v133, v132
	s_nop 0
	v_add_u32_e32 v134, -1, v133
	v_fma_f32 v135, -v134, v133, v132
	v_cmp_ge_f32_e64 s[0:1], 0, v135
	v_add_u32_e32 v135, 1, v133
	s_nop 0
	v_cndmask_b32_e64 v134, v133, v134, s[0:1]
	v_fma_f32 v133, -v135, v133, v132
	v_cmp_lt_f32_e64 s[0:1], 0, v133
	s_nop 1
	v_cndmask_b32_e64 v133, v134, v135, s[0:1]
	v_mul_f32_e32 v134, 0x37800000, v133
	v_cndmask_b32_e32 v133, v133, v134, vcc
	v_cmp_class_f32_e32 vcc, v132, v210
	s_nop 1
	v_cndmask_b32_e32 v132, v133, v132, vcc
	v_div_scale_f32 v133, s[0:1], v132, v132, 1.0
	v_rcp_f32_e32 v134, v133
	s_nop 0
	v_fma_f32 v135, -v133, v134, 1.0
	v_fmac_f32_e32 v134, v135, v134
	v_div_scale_f32 v135, vcc, 1.0, v132, 1.0
	v_mul_f32_e32 v136, v135, v134
	v_fma_f32 v137, -v133, v136, v135
	v_fmac_f32_e32 v136, v137, v134
	v_fma_f32 v133, -v133, v136, v135
	v_div_fmas_f32 v133, v133, v134, v136
	v_div_fixup_f32 v191, v133, v132, 1.0
	s_waitcnt vmcnt(0)
	v_mov_b64_e32 v[132:133], v[194:195]
	v_mov_b64_e32 v[134:135], v[196:197]
	v_mov_b64_e32 v[136:137], v[198:199]
	v_mov_b64_e32 v[138:139], v[200:201]
	v_mov_b64_e32 v[140:141], v[202:203]
	v_mov_b64_e32 v[142:143], v[204:205]
	v_mov_b64_e32 v[168:169], v[214:215]
	v_mov_b64_e32 v[170:171], v[216:217]
	v_add_f32_e32 v136, v136, v137
	v_add_f32_e32 v138, v138, v139
	v_mov_b32_e32 v172, v169
	v_mov_b32_e32 v173, v170
	v_mov_b32_e32 v169, v171
	v_mov_b32_e32 v170, v141
	v_mov_b32_e32 v171, v142
	v_mov_b32_e32 v141, v143
	v_pk_add_f32 v[168:169], v[172:173], v[168:169]
	v_pk_add_f32 v[140:141], v[170:171], v[140:141]
	v_pk_add_f32 v[168:169], v[168:169], v[168:169] op_sel:[0,1] op_sel_hi:[1,0]
	v_pk_add_f32 v[140:141], v[140:141], v[140:141] op_sel:[0,1] op_sel_hi:[1,0]
	v_mov_b32_e32 v169, v132
	v_mov_b32_e32 v141, v133
	v_mov_b32_e32 v137, v134
	v_mov_b32_e32 v139, v135
	v_pk_add_f32 v[132:133], v[168:169], v[140:141]
	v_pk_add_f32 v[134:135], v[136:137], v[138:139]
	s_nop 0
	v_pk_add_f32 v[132:133], v[132:133], v[134:135]
	s_nop 0
	v_add_f32_e32 v132, v132, v133
	v_fmamk_f32 v132, v132, 0x3a800000, v209
	v_cmp_gt_f32_e32 vcc, s20, v132
	v_mul_f32_e32 v133, 0x4f800000, v132
	s_nop 0
	v_cndmask_b32_e32 v132, v132, v133, vcc
	v_sqrt_f32_e32 v133, v132
	s_nop 0
	v_add_u32_e32 v134, -1, v133
	v_fma_f32 v135, -v134, v133, v132
	v_cmp_ge_f32_e64 s[0:1], 0, v135
	v_add_u32_e32 v135, 1, v133
	s_nop 0
	v_cndmask_b32_e64 v134, v133, v134, s[0:1]
	v_fma_f32 v133, -v135, v133, v132
	v_cmp_lt_f32_e64 s[0:1], 0, v133
	s_nop 1
	v_cndmask_b32_e64 v133, v134, v135, s[0:1]
	v_mul_f32_e32 v134, 0x37800000, v133
	v_cndmask_b32_e32 v133, v133, v134, vcc
	v_cmp_class_f32_e32 vcc, v132, v210
	s_nop 1
	v_cndmask_b32_e32 v132, v133, v132, vcc
	v_div_scale_f32 v133, s[0:1], v132, v132, 1.0
	v_rcp_f32_e32 v134, v133
	s_nop 0
	v_fma_f32 v135, -v133, v134, 1.0
	v_fmac_f32_e32 v134, v135, v134
	v_div_scale_f32 v135, vcc, 1.0, v132, 1.0
	v_mul_f32_e32 v136, v135, v134
	v_fma_f32 v137, -v133, v136, v135
	v_fmac_f32_e32 v136, v137, v134
	v_fma_f32 v133, -v133, v136, v135
	v_div_fmas_f32 v133, v133, v134, v136
	v_div_fixup_f32 v192, v133, v132, 1.0
	s_branch .LBB0_438

.LBB0_467:
	s_cmpk_lg_i32 s44, 0x100
	s_cbranch_scc1 .LBB0_466
	global_load_dwordx4 v[158:161], v[144:145], off
	global_load_dwordx4 v[162:165], v[144:145], off offset:16
	global_load_dwordx4 v[188:191], v[146:147], off
	global_load_dwordx4 v[192:195], v[146:147], off offset:16
	s_waitcnt vmcnt(2)
	v_mov_b32_e32 v166, v158
	v_mov_b32_e32 v167, v162
	v_mov_b32_e32 v162, v159
	v_pk_add_f32 v[158:159], v[166:167], v[162:163]
	v_mov_b32_e32 v162, v160
	v_mov_b32_e32 v163, v164
	v_mov_b32_e32 v164, v161
	v_pk_add_f32 v[160:161], v[162:163], v[164:165]
	s_nop 0
	v_pk_add_f32 v[158:159], v[158:159], v[160:161]
	s_nop 0
	v_add_f32_e32 v157, v158, v159
	v_fmamk_f32 v157, v157, 0x3b000000, v209
	v_cmp_gt_f32_e32 vcc, s20, v157
	v_mul_f32_e32 v158, 0x4f800000, v157
	s_nop 0
	v_cndmask_b32_e32 v157, v157, v158, vcc
	v_sqrt_f32_e32 v158, v157
	s_nop 0
	v_add_u32_e32 v159, -1, v158
	v_fma_f32 v160, -v159, v158, v157
	v_cmp_ge_f32_e64 s[0:1], 0, v160
	v_add_u32_e32 v160, 1, v158
	s_nop 0
	v_cndmask_b32_e64 v159, v158, v159, s[0:1]
	v_fma_f32 v158, -v160, v158, v157
	v_cmp_lt_f32_e64 s[0:1], 0, v158
	s_nop 1
	v_cndmask_b32_e64 v158, v159, v160, s[0:1]
	v_mul_f32_e32 v159, 0x37800000, v158
	v_cndmask_b32_e32 v158, v158, v159, vcc
	v_cmp_class_f32_e32 vcc, v157, v210
	s_nop 1
	v_cndmask_b32_e32 v157, v158, v157, vcc
	v_div_scale_f32 v158, s[0:1], v157, v157, 1.0
	v_rcp_f32_e32 v159, v158
	s_nop 0
	v_fma_f32 v160, -v158, v159, 1.0
	v_fmac_f32_e32 v159, v160, v159
	v_div_scale_f32 v160, vcc, 1.0, v157, 1.0
	v_mul_f32_e32 v161, v160, v159
	v_fma_f32 v162, -v158, v161, v160
	v_fmac_f32_e32 v161, v162, v159
	v_fma_f32 v158, -v158, v161, v160
	v_div_fmas_f32 v158, v158, v159, v161
	v_div_fixup_f32 v157, v158, v157, 1.0
	s_waitcnt vmcnt(0)
	v_mov_b64_e32 v[158:159], v[188:189]
	v_mov_b64_e32 v[160:161], v[190:191]
	v_mov_b64_e32 v[162:163], v[192:193]
	v_mov_b64_e32 v[164:165], v[194:195]
	s_waitcnt vmcnt(1)
	v_mov_b32_e32 v166, v158
	s_waitcnt vmcnt(0)
	v_mov_b32_e32 v167, v162
	v_mov_b32_e32 v162, v159
	v_pk_add_f32 v[158:159], v[166:167], v[162:163]
	v_mov_b32_e32 v162, v160
	v_mov_b32_e32 v163, v164
	v_mov_b32_e32 v164, v161
	v_pk_add_f32 v[160:161], v[162:163], v[164:165]
	s_nop 0
	v_pk_add_f32 v[158:159], v[158:159], v[160:161]
	s_nop 0
	v_add_f32_e32 v158, v158, v159
	v_fmamk_f32 v158, v158, 0x3b000000, v209
	v_cmp_gt_f32_e32 vcc, s20, v158
	v_mul_f32_e32 v159, 0x4f800000, v158
	s_nop 0
	v_cndmask_b32_e32 v158, v158, v159, vcc
	v_sqrt_f32_e32 v159, v158
	s_nop 0
	v_add_u32_e32 v160, -1, v159
	v_fma_f32 v161, -v160, v159, v158
	v_cmp_ge_f32_e64 s[0:1], 0, v161
	v_add_u32_e32 v161, 1, v159
	s_nop 0
	v_cndmask_b32_e64 v160, v159, v160, s[0:1]
	v_fma_f32 v159, -v161, v159, v158
	v_cmp_lt_f32_e64 s[0:1], 0, v159
	s_nop 1
	v_cndmask_b32_e64 v159, v160, v161, s[0:1]
	v_mul_f32_e32 v160, 0x37800000, v159
	v_cndmask_b32_e32 v159, v159, v160, vcc
	v_cmp_class_f32_e32 vcc, v158, v210
	s_nop 1
	v_cndmask_b32_e32 v158, v159, v158, vcc
	v_div_scale_f32 v159, s[0:1], v158, v158, 1.0
	v_rcp_f32_e32 v160, v159
	s_nop 0
	v_fma_f32 v161, -v159, v160, 1.0
	v_fmac_f32_e32 v160, v161, v160
	v_div_scale_f32 v161, vcc, 1.0, v158, 1.0
	v_mul_f32_e32 v162, v161, v160
	v_fma_f32 v163, -v159, v162, v161
	v_fmac_f32_e32 v162, v163, v160
	v_fma_f32 v159, -v159, v162, v161
	v_div_fmas_f32 v159, v159, v160, v162
	v_div_fixup_f32 v158, v159, v158, 1.0
	s_branch .LBB0_466
